# P6 GroupNorm/gate epilogue: 32 gate/gain loads issued up front with counted waits (was load-wait-store per 8 columns)
# speedup vs baseline: 1.0055x; 1.0020x over previous
; __device__ __forceinline__ int crow(int r, int hi) { return (r & 3) + 8 * (r >> 2) + 4 * hi; }
; #define MFMA32(a, b, c) __builtin_amdgcn_mfma_f32_32x32x16_bf16((a), (b), (c), 0, 0, 0)
; __device__ __forceinline__ void ro_item2(int it0, LAS unsigned char* lds, const bf16_t* RQ, const bf16_t* RK, const bf16_t* RV, const bf16_t* RG, const bf16_t* SPREV, const float* GN, bf16_t* MIX,
;                                          int tid, int wid, int lane) {
;     ...
;     for (int jt = 0; jt <= ct; ++jt) {
;         f32x16 st = {};
;         const bf16_t* kptr = RK + (r0 + 32 * jt + x) * 1024 + h * 128 + 8 * hi;
; #pragma unroll
;         for (int ks = 0; ks < 8; ++ks) st = MFMA32(*(const bf16x8*)(kptr + 16 * ks), qf[ks], st);
;         if (jt == ct) {
; #pragma unroll
;             for (int r = 0; r < 16; ++r) if (crow(r, hi) > x) st[r] = 0.f;
;         }
; #pragma unroll
;         for (int s2 = 0; s2 < 2; ++s2) {
;             const bf16x8 pb = pack8(st, s2);
; #pragma unroll
;             for (int et = 0; et < 4; ++et) o[et] = MFMA32(lds_cat_sw<VS>(VT, 32 * et + x, 32 * jt + 16 * s2 + 4 * hi), pb, o[et]);
;         }
;     }
;     const bf16_t* sp = SPREV + (size_t)it * 16384;
; #pragma unroll
;     for (int et = 0; et < 4; ++et)
; #pragma unroll
;         for (int ks = 0; ks < 8; ++ks) o[et] = MFMA32(*(const bf16x8*)(sp + (32 * et + x) * 128 + 16 * ks + 8 * hi), qf[ks], o[et]);
.LBB0_1219:
	v_mov_b32_e32 v68, s53
	v_or3_b32 v69, s48, 0, 0
	v_or3_b32 v68, s35, v126, v68
	v_lshl_add_u64 v[66:67], v[130:131], 0, s[42:43]
	v_lshlrev_b64 v[68:69], 11, v[68:69]
	v_lshl_add_u64 v[146:147], v[66:67], 0, v[68:69]
	s_ashr_i32 s35, s34, 31
	s_lshl_b64 s[34:35], s[34:35], 15
	s_add_i32 s50, s50, s54
	s_add_i32 s55, s55, s56
	s_add_i32 s57, s57, s58
	s_mov_b64 s[100:101], 0x2000
	v_lshl_add_u64 v[184:185], v[134:135], 0, s[34:35]
	v_lshl_add_u64 v[186:187], v[184:185], 0, s[100:101]
	v_lshl_add_u64 v[188:189], v[186:187], 0, s[100:101]
	v_lshl_add_u64 v[252:253], v[188:189], 0, s[100:101]
	global_load_dwordx4 v[192:195], v[184:185], off
	global_load_dwordx4 v[196:199], v[184:185], off offset:32
	global_load_dwordx4 v[200:203], v[184:185], off offset:64
	global_load_dwordx4 v[204:207], v[184:185], off offset:96
	global_load_dwordx4 v[208:211], v[184:185], off offset:128
	global_load_dwordx4 v[212:215], v[184:185], off offset:160
	global_load_dwordx4 v[216:219], v[184:185], off offset:192
	global_load_dwordx4 v[220:223], v[146:147], off
	global_load_dwordx4 v[224:227], v[146:147], off offset:32
	global_load_dwordx4 v[228:231], v[146:147], off offset:64
	global_load_dwordx4 v[232:235], v[146:147], off offset:96
	global_load_dwordx4 v[236:239], v[146:147], off offset:128
	global_load_dwordx4 v[240:243], v[146:147], off offset:160
	global_load_dwordx4 v[244:247], v[146:147], off offset:192
	global_load_dwordx4 v[248:251], v[146:147], off offset:224
	s_waitcnt vmcnt(7)
	v_mfma_f32_32x32x16_bf16 v[66:81], v[220:223], v[110:113], 0
	s_waitcnt vmcnt(6)
	v_mfma_f32_32x32x16_bf16 v[66:81], v[224:227], v[106:109], v[66:81]
	s_waitcnt vmcnt(5)
	v_mfma_f32_32x32x16_bf16 v[66:81], v[228:231], v[102:105], v[66:81]
	s_waitcnt vmcnt(4)
	v_mfma_f32_32x32x16_bf16 v[66:81], v[232:235], v[98:101], v[66:81]
	s_waitcnt vmcnt(3)
	v_mfma_f32_32x32x16_bf16 v[66:81], v[236:239], v[94:97], v[66:81]
	s_waitcnt vmcnt(2)
	v_mfma_f32_32x32x16_bf16 v[66:81], v[240:243], v[90:93], v[66:81]
	s_waitcnt vmcnt(1)
	v_mfma_f32_32x32x16_bf16 v[66:81], v[244:247], v[86:89], v[66:81]
	s_waitcnt vmcnt(0)
	v_mfma_f32_32x32x16_bf16 v[66:81], v[248:251], v[82:85], v[66:81]
	global_load_dwordx4 v[220:223], v[184:185], off offset:224
	global_load_dwordx4 v[224:227], v[186:187], off
	global_load_dwordx4 v[228:231], v[186:187], off offset:32
	global_load_dwordx4 v[232:235], v[186:187], off offset:64
	global_load_dwordx4 v[236:239], v[186:187], off offset:96
	global_load_dwordx4 v[240:243], v[186:187], off offset:128
	global_load_dwordx4 v[244:247], v[186:187], off offset:160
	global_load_dwordx4 v[248:251], v[186:187], off offset:192
	s_nop 11
	v_cndmask_b32_e64 v141, v66, 0, s[0:1]
	v_cndmask_b32_e64 v66, v141, v66, s[2:3]
	v_cndmask_b32_e64 v67, 0, v67, s[2:3]
	v_cndmask_b32_e64 v68, v68, 0, s[4:5]
	v_cndmask_b32_e64 v69, v69, 0, s[6:7]
	v_cndmask_b32_e64 v70, v70, 0, s[8:9]
	v_cndmask_b32_e64 v71, v71, 0, s[10:11]
	v_cndmask_b32_e64 v72, v72, 0, s[12:13]
	v_cndmask_b32_e64 v73, v73, 0, s[14:15]
	v_cvt_pk_bf16_f32 v66, v66, v67
	v_cvt_pk_bf16_f32 v67, v68, v69
	v_cvt_pk_bf16_f32 v68, v70, v71
	v_cvt_pk_bf16_f32 v69, v72, v73
	ds_read_b64 v[70:71], v157
	ds_read_b64 v[72:73], v158
	s_waitcnt lgkmcnt(0)
	v_mfma_f32_32x32x16_bf16 v[50:65], v[70:73], v[66:69], v[50:65]
	ds_read_b64 v[70:71], v159
	ds_read_b64 v[72:73], v160
	v_cndmask_b32_e64 v74, v74, 0, s[16:17]
	v_cndmask_b32_e64 v75, v75, 0, s[18:19]
	v_cndmask_b32_e64 v76, v76, 0, s[20:21]
	v_cndmask_b32_e64 v77, v77, 0, s[22:23]
	v_cndmask_b32_e64 v78, v78, 0, s[24:25]
	v_cndmask_b32_e64 v79, v79, 0, s[26:27]
	s_waitcnt lgkmcnt(0)
	v_mfma_f32_32x32x16_bf16 v[34:49], v[70:73], v[66:69], v[34:49]
	ds_read_b64 v[70:71], v161
	ds_read_b64 v[72:73], v162
	v_cndmask_b32_e64 v80, v80, 0, s[28:29]
	v_cndmask_b32_e64 v81, v81, 0, s[30:31]
	v_mov_b32_e32 v141, v115
	s_waitcnt lgkmcnt(0)
	v_mfma_f32_32x32x16_bf16 v[18:33], v[70:73], v[66:69], v[18:33]
	ds_read_b64 v[70:71], v163
	ds_read_b64 v[72:73], v164
	s_waitcnt lgkmcnt(0)
	v_mfma_f32_32x32x16_bf16 v[2:17], v[70:73], v[66:69], v[2:17]
	ds_read_b64 v[70:71], v165
	ds_read_b64 v[72:73], v166
	v_cvt_pk_bf16_f32 v66, v74, v75
	v_cvt_pk_bf16_f32 v67, v76, v77
	v_cvt_pk_bf16_f32 v68, v78, v79
	v_cvt_pk_bf16_f32 v69, v80, v81
	s_waitcnt lgkmcnt(0)
	s_nop 0
	v_mfma_f32_32x32x16_bf16 v[50:65], v[70:73], v[66:69], v[50:65]
	ds_read_b64 v[70:71], v167
	ds_read_b64 v[72:73], v168
	s_waitcnt lgkmcnt(0)
	v_mfma_f32_32x32x16_bf16 v[34:49], v[70:73], v[66:69], v[34:49]
	ds_read_b64 v[70:71], v169
	ds_read_b64 v[72:73], v170
	s_waitcnt lgkmcnt(0)
	v_mfma_f32_32x32x16_bf16 v[18:33], v[70:73], v[66:69], v[18:33]
	ds_read_b64 v[70:71], v171
	ds_read_b64 v[72:73], v172
	s_waitcnt lgkmcnt(0)
	v_mfma_f32_32x32x16_bf16 v[2:17], v[70:73], v[66:69], v[2:17]
	s_waitcnt vmcnt(14)
	v_mfma_f32_32x32x16_bf16 v[50:65], v[192:195], v[110:113], v[50:65]
	global_load_dwordx4 v[192:195], v[186:187], off offset:224
	s_waitcnt vmcnt(14)
	v_mfma_f32_32x32x16_bf16 v[50:65], v[196:199], v[106:109], v[50:65]
	global_load_dwordx4 v[196:199], v[188:189], off
	s_waitcnt vmcnt(14)
	v_mfma_f32_32x32x16_bf16 v[50:65], v[200:203], v[102:105], v[50:65]
	global_load_dwordx4 v[200:203], v[188:189], off offset:32
	s_waitcnt vmcnt(14)
	v_mfma_f32_32x32x16_bf16 v[50:65], v[204:207], v[98:101], v[50:65]
	global_load_dwordx4 v[204:207], v[188:189], off offset:64
	s_waitcnt vmcnt(14)
	v_mfma_f32_32x32x16_bf16 v[50:65], v[208:211], v[94:97], v[50:65]
	global_load_dwordx4 v[208:211], v[188:189], off offset:96
	s_waitcnt vmcnt(14)
	v_mfma_f32_32x32x16_bf16 v[50:65], v[212:215], v[90:93], v[50:65]
	global_load_dwordx4 v[212:215], v[188:189], off offset:128
	s_waitcnt vmcnt(14)
; #define MFMA32(a, b, c) __builtin_amdgcn_mfma_f32_32x32x16_bf16((a), (b), (c), 0, 0, 0)
; __device__ __forceinline__ void ro_item2(int it0, LAS unsigned char* lds, const bf16_t* RQ, const bf16_t* RK, const bf16_t* RV, const bf16_t* RG, const bf16_t* SPREV, const float* GN, bf16_t* MIX,
;                                          int tid, int wid, int lane) {
;     ...
;     const bf16_t* sp = SPREV + (size_t)it * 16384;
; #pragma unroll
;     for (int et = 0; et < 4; ++et)
; #pragma unroll
;         for (int ks = 0; ks < 8; ++ks) o[et] = MFMA32(*(const bf16x8*)(sp + (32 * et + x) * 128 + 16 * ks + 8 * hi), qf[ks], o[et]);
;     float s1 = 0.f, s2 = 0.f;
; #pragma unroll
;     for (int et = 0; et < 4; ++et)
; #pragma unroll
;         for (int r = 0; r < 16; ++r) { s1 += o[et][r]; s2 += o[et][r] * o[et][r]; }
	v_mfma_f32_32x32x16_bf16 v[50:65], v[216:219], v[86:89], v[50:65]
	global_load_dwordx4 v[216:219], v[188:189], off offset:160
	s_waitcnt vmcnt(14)
	v_mfma_f32_32x32x16_bf16 v[50:65], v[220:223], v[82:85], v[50:65]
	global_load_dwordx4 v[220:223], v[188:189], off offset:192
	s_waitcnt vmcnt(14)
	v_mfma_f32_32x32x16_bf16 v[34:49], v[224:227], v[110:113], v[34:49]
	global_load_dwordx4 v[224:227], v[188:189], off offset:224
	s_nop 8
	v_mul_f32_e32 v80, v51, v51
	v_fmac_f32_e32 v80, v50, v50
	v_fmac_f32_e32 v80, v52, v52
	v_fmac_f32_e32 v80, v53, v53
	v_fmac_f32_e32 v80, v54, v54
	v_fmac_f32_e32 v80, v55, v55
	v_fmac_f32_e32 v80, v56, v56
	v_fmac_f32_e32 v80, v57, v57
	v_fmac_f32_e32 v80, v58, v58
	v_fmac_f32_e32 v80, v59, v59
	v_fmac_f32_e32 v80, v60, v60
	v_fmac_f32_e32 v80, v61, v61
	v_fmac_f32_e32 v80, v62, v62
	v_fmac_f32_e32 v80, v63, v63
	v_fmac_f32_e32 v80, v64, v64
	v_fmac_f32_e32 v80, v65, v65
	s_waitcnt vmcnt(14)
	v_mfma_f32_32x32x16_bf16 v[34:49], v[228:231], v[106:109], v[34:49]
	global_load_dwordx4 v[228:231], v[252:253], off
	s_waitcnt vmcnt(14)
	v_mfma_f32_32x32x16_bf16 v[34:49], v[232:235], v[102:105], v[34:49]
	global_load_dwordx4 v[232:235], v[252:253], off offset:32
	s_waitcnt vmcnt(14)
	v_mfma_f32_32x32x16_bf16 v[34:49], v[236:239], v[98:101], v[34:49]
	global_load_dwordx4 v[236:239], v[252:253], off offset:64
	s_waitcnt vmcnt(14)
	v_mfma_f32_32x32x16_bf16 v[34:49], v[240:243], v[94:97], v[34:49]
	global_load_dwordx4 v[240:243], v[252:253], off offset:96
	s_waitcnt vmcnt(14)
	v_mfma_f32_32x32x16_bf16 v[34:49], v[244:247], v[90:93], v[34:49]
	global_load_dwordx4 v[244:247], v[252:253], off offset:128
	s_waitcnt vmcnt(14)
	v_mfma_f32_32x32x16_bf16 v[34:49], v[248:251], v[86:89], v[34:49]
	global_load_dwordx4 v[248:251], v[252:253], off offset:160
	s_waitcnt vmcnt(14)
	v_mfma_f32_32x32x16_bf16 v[34:49], v[192:195], v[82:85], v[34:49]
	global_load_dwordx4 v[192:195], v[252:253], off offset:192
	s_waitcnt vmcnt(14)
	v_mfma_f32_32x32x16_bf16 v[18:33], v[196:199], v[110:113], v[18:33]
	global_load_dwordx4 v[196:199], v[252:253], off offset:224
	s_nop 8
	v_fmac_f32_e32 v80, v34, v34
	v_fmac_f32_e32 v80, v35, v35
	v_fmac_f32_e32 v80, v36, v36
	v_fmac_f32_e32 v80, v37, v37
	v_fmac_f32_e32 v80, v38, v38
	v_fmac_f32_e32 v80, v39, v39
	v_fmac_f32_e32 v80, v40, v40
	v_fmac_f32_e32 v80, v41, v41
	v_fmac_f32_e32 v80, v42, v42
	v_fmac_f32_e32 v80, v43, v43
	v_fmac_f32_e32 v80, v44, v44
	v_fmac_f32_e32 v80, v45, v45
	v_fmac_f32_e32 v80, v46, v46
	v_fmac_f32_e32 v80, v47, v47
	v_fmac_f32_e32 v80, v48, v48
	v_fmac_f32_e32 v80, v49, v49
	s_waitcnt vmcnt(14)
	v_mfma_f32_32x32x16_bf16 v[18:33], v[200:203], v[106:109], v[18:33]
	s_waitcnt vmcnt(13)
	v_mfma_f32_32x32x16_bf16 v[18:33], v[204:207], v[102:105], v[18:33]
	s_waitcnt vmcnt(12)
	v_mfma_f32_32x32x16_bf16 v[18:33], v[208:211], v[98:101], v[18:33]
	s_waitcnt vmcnt(11)
	v_mfma_f32_32x32x16_bf16 v[18:33], v[212:215], v[94:97], v[18:33]
	s_waitcnt vmcnt(10)
	v_mfma_f32_32x32x16_bf16 v[18:33], v[216:219], v[90:93], v[18:33]
	s_waitcnt vmcnt(9)
	v_mfma_f32_32x32x16_bf16 v[18:33], v[220:223], v[86:89], v[18:33]
	s_waitcnt vmcnt(8)
	v_mfma_f32_32x32x16_bf16 v[18:33], v[224:227], v[82:85], v[18:33]
	s_waitcnt vmcnt(7)
	v_mfma_f32_32x32x16_bf16 v[2:17], v[228:231], v[110:113], v[2:17]
	s_nop 8
	v_fmac_f32_e32 v80, v18, v18
	v_fmac_f32_e32 v80, v19, v19
	v_fmac_f32_e32 v80, v20, v20
	v_fmac_f32_e32 v80, v21, v21
	v_fmac_f32_e32 v80, v22, v22
	v_fmac_f32_e32 v80, v23, v23
	v_fmac_f32_e32 v80, v24, v24
	v_fmac_f32_e32 v80, v25, v25
	v_fmac_f32_e32 v80, v26, v26
	v_fmac_f32_e32 v80, v27, v27
	v_fmac_f32_e32 v80, v28, v28
	v_fmac_f32_e32 v80, v29, v29
	v_fmac_f32_e32 v80, v30, v30
	v_fmac_f32_e32 v80, v31, v31
	v_fmac_f32_e32 v80, v32, v32
	v_fmac_f32_e32 v80, v33, v33
	s_waitcnt vmcnt(6)
	v_mfma_f32_32x32x16_bf16 v[2:17], v[232:235], v[106:109], v[2:17]
	s_waitcnt vmcnt(5)
	v_mfma_f32_32x32x16_bf16 v[2:17], v[236:239], v[102:105], v[2:17]
	s_waitcnt vmcnt(4)
	v_mfma_f32_32x32x16_bf16 v[2:17], v[240:243], v[98:101], v[2:17]
	s_waitcnt vmcnt(3)
	v_mfma_f32_32x32x16_bf16 v[2:17], v[244:247], v[94:97], v[2:17]
	s_waitcnt vmcnt(2)
	v_mfma_f32_32x32x16_bf16 v[2:17], v[248:251], v[90:93], v[2:17]
	s_waitcnt vmcnt(1)
	v_mfma_f32_32x32x16_bf16 v[2:17], v[192:195], v[86:89], v[2:17]
	s_waitcnt vmcnt(0)
; __device__ __forceinline__ void ro_item2(int it0, LAS unsigned char* lds, const bf16_t* RQ, const bf16_t* RK, const bf16_t* RV, const bf16_t* RG, const bf16_t* SPREV, const float* GN, bf16_t* MIX,
;                                          int tid, int wid, int lane) {
;     ...
;     float s1 = 0.f, s2 = 0.f;
; #pragma unroll
;     for (int et = 0; et < 4; ++et)
; #pragma unroll
;         for (int r = 0; r < 16; ++r) { s1 += o[et][r]; s2 += o[et][r] * o[et][r]; }
;     s1 += __shfl_xor(s1, 32); s2 += __shfl_xor(s2, 32);
;     const float mean = s1 * (1.0f / 128.0f), var = fmaxf(s2 * (1.0f / 128.0f) - mean * mean, 0.f), rstd = rsqrtf(var + EPS);
; #pragma unroll
;     for (int et = 0; et < 4; ++et)
; #pragma unroll
;         for (int g = 0; g < 4; ++g) {
;             const int e0 = 32 * et + 8 * g + 4 * hi;
;             const u32x2 gt = *(const u32x2*)(RG + qrow * 1024 + h * 128 + e0);
;             const f32x4 gn = *(const f32x4*)(GN + h * 128 + e0);
	v_mfma_f32_32x32x16_bf16 v[2:17], v[196:199], v[82:85], v[2:17]
	s_brev_b32 s34, 60
	v_add_f32_e32 v66, 0, v50
	v_add_f32_e32 v66, v51, v66
	v_add_f32_e32 v66, v52, v66
	v_add_f32_e32 v66, v53, v66
	v_add_f32_e32 v66, v54, v66
	v_add_f32_e32 v66, v55, v66
	v_add_f32_e32 v66, v56, v66
	v_add_f32_e32 v66, v57, v66
	v_add_f32_e32 v66, v58, v66
	v_add_f32_e32 v66, v59, v66
	v_add_f32_e32 v66, v60, v66
	v_add_f32_e32 v66, v61, v66
	v_add_f32_e32 v66, v62, v66
	v_add_f32_e32 v66, v63, v66
	v_add_f32_e32 v66, v64, v66
	v_add_f32_e32 v66, v65, v66
	v_add_f32_e32 v66, v66, v34
	v_add_f32_e32 v66, v35, v66
	v_add_f32_e32 v66, v36, v66
	v_add_f32_e32 v66, v37, v66
	v_add_f32_e32 v66, v38, v66
	v_add_f32_e32 v66, v39, v66
	v_add_f32_e32 v66, v40, v66
	v_add_f32_e32 v66, v41, v66
	v_add_f32_e32 v66, v42, v66
	v_add_f32_e32 v66, v43, v66
	v_add_f32_e32 v66, v44, v66
	v_add_f32_e32 v66, v45, v66
	v_add_f32_e32 v66, v46, v66
	v_add_f32_e32 v66, v47, v66
	v_add_f32_e32 v66, v48, v66
	v_add_f32_e32 v66, v49, v66
	v_add_f32_e32 v66, v66, v18
	v_add_f32_e32 v66, v19, v66
	v_add_f32_e32 v66, v20, v66
	v_add_f32_e32 v66, v21, v66
	v_add_f32_e32 v66, v22, v66
	v_add_f32_e32 v66, v23, v66
	v_add_f32_e32 v66, v24, v66
	v_add_f32_e32 v66, v25, v66
	v_add_f32_e32 v66, v26, v66
	v_add_f32_e32 v66, v27, v66
	v_add_f32_e32 v66, v28, v66
	v_add_f32_e32 v66, v29, v66
	v_add_f32_e32 v66, v30, v66
	v_add_f32_e32 v66, v31, v66
	v_add_f32_e32 v66, v32, v66
	v_add_f32_e32 v66, v33, v66
	v_add_f32_e32 v66, v66, v2
	v_add_f32_e32 v66, v3, v66
	v_fmac_f32_e32 v80, v2, v2
	v_add_f32_e32 v66, v4, v66
	v_fmac_f32_e32 v80, v3, v3
	v_add_f32_e32 v66, v5, v66
	v_fmac_f32_e32 v80, v4, v4
	v_add_f32_e32 v81, v6, v66
	v_pk_mul_f32 v[66:67], v[16:17], v[16:17]
	v_pk_mul_f32 v[78:79], v[4:5], v[4:5]
	v_pk_mul_f32 v[76:77], v[6:7], v[6:7]
	v_add_f32_e32 v67, v79, v80
	v_add_f32_e32 v67, v76, v67
	v_pk_mul_f32 v[74:75], v[8:9], v[8:9]
	v_add_f32_e32 v76, v7, v81
	v_add_f32_e32 v67, v77, v67
	v_add_f32_e32 v76, v8, v76
	v_add_f32_e32 v67, v74, v67
	v_pk_mul_f32 v[72:73], v[10:11], v[10:11]
	v_add_f32_e32 v74, v9, v76
	v_add_f32_e32 v67, v75, v67
	v_add_f32_e32 v74, v10, v74
	v_add_f32_e32 v67, v72, v67
	v_pk_mul_f32 v[70:71], v[12:13], v[12:13]
	v_add_f32_e32 v72, v11, v74
	v_add_f32_e32 v67, v73, v67
	v_add_f32_e32 v72, v12, v72
	v_add_f32_e32 v67, v70, v67
	v_pk_mul_f32 v[68:69], v[14:15], v[14:15]
	v_add_f32_e32 v70, v13, v72
	v_add_f32_e32 v67, v71, v67
	v_add_f32_e32 v70, v14, v70
	v_add_f32_e32 v68, v68, v67
	v_add_f32_e32 v67, v15, v70
	v_add_f32_e32 v68, v69, v68
	v_add_f32_e32 v67, v16, v67
	v_add_f32_e32 v68, v66, v68
	v_mul_f32_e32 v66, v17, v17
	v_mov_b32_e32 v69, v17
	v_pk_add_f32 v[66:67], v[68:69], v[66:67]
	ds_bpermute_b32 v69, v173, v67
	ds_bpermute_b32 v68, v173, v66
	s_waitcnt lgkmcnt(0)
	v_pk_add_f32 v[66:67], v[66:67], v[68:69]
	s_nop 0
	v_pk_mul_f32 v[70:71], v[66:67], s[34:35] op_sel_hi:[1,0]
	s_mov_b32 s34, 0x800000
	v_fma_f32 v66, -v71, v71, v70
	v_max_f32_e32 v66, 0, v66
	v_add_f32_e32 v66, 0x358637bd, v66
	v_cmp_gt_f32_e32 vcc, s34, v66
	v_mul_f32_e32 v67, 0x4b800000, v66
	v_readlane_b32 s34, v254, 54
	v_cndmask_b32_e32 v66, v66, v67, vcc
	v_rsq_f32_e32 v66, v66
	v_readlane_b32 s35, v254, 55
	v_lshlrev_b64 v[68:69], 12, v[142:143]
	v_lshl_add_u64 v[68:69], s[38:39], 0, v[68:69]
	v_mul_f32_e32 v67, 0x45800000, v66
	v_cndmask_b32_e32 v72, v66, v67, vcc
	v_lshl_add_u64 v[66:67], s[34:35], 0, v[144:145]
	v_lshl_add_u64 v[66:67], v[66:67], 0, s[42:43]
	v_lshl_add_u64 v[78:79], v[68:69], 0, s[42:43]
	s_lshl_b32 s42, s33, 2
	v_lshl_add_u64 v[76:77], v[66:67], 0, v[140:141]
	v_lshl_add_u64 v[74:75], v[136:137], 0, s[42:43]
	global_load_dwordx2 v[82:83], v[76:77], off
	global_load_dwordx4 v[192:195], v[74:75], off
	global_load_dwordx2 v[84:85], v[76:77], off offset:16
	global_load_dwordx4 v[196:199], v[74:75], off offset:32
	global_load_dwordx2 v[86:87], v[76:77], off offset:32
	global_load_dwordx4 v[200:203], v[74:75], off offset:64
	global_load_dwordx2 v[88:89], v[76:77], off offset:48
	global_load_dwordx4 v[204:207], v[74:75], off offset:96
	global_load_dwordx2 v[90:91], v[76:77], off offset:64
	global_load_dwordx4 v[208:211], v[74:75], off offset:128
	global_load_dwordx2 v[92:93], v[76:77], off offset:80
	global_load_dwordx4 v[212:215], v[74:75], off offset:160
	global_load_dwordx2 v[94:95], v[76:77], off offset:96
	global_load_dwordx4 v[216:219], v[74:75], off offset:192
	global_load_dwordx2 v[96:97], v[76:77], off offset:112
	global_load_dwordx4 v[220:223], v[74:75], off offset:224
	global_load_dwordx2 v[98:99], v[76:77], off offset:128
	global_load_dwordx4 v[224:227], v[74:75], off offset:256
	global_load_dwordx2 v[100:101], v[76:77], off offset:144
	global_load_dwordx4 v[228:231], v[74:75], off offset:288
	global_load_dwordx2 v[102:103], v[76:77], off offset:160
	global_load_dwordx4 v[232:235], v[74:75], off offset:320
	global_load_dwordx2 v[104:105], v[76:77], off offset:176
	global_load_dwordx4 v[236:239], v[74:75], off offset:352
	global_load_dwordx2 v[106:107], v[76:77], off offset:192
	global_load_dwordx4 v[240:243], v[74:75], off offset:384
	global_load_dwordx2 v[108:109], v[76:77], off offset:208
	global_load_dwordx4 v[244:247], v[74:75], off offset:416
	global_load_dwordx2 v[110:111], v[76:77], off offset:224
	global_load_dwordx4 v[248:251], v[74:75], off offset:448
	global_load_dwordx2 v[112:113], v[76:77], off offset:240
	global_load_dwordx4 v[180:183], v[74:75], off offset:480
	v_pk_add_f32 v[50:51], v[50:51], v[70:71] op_sel:[0,1] neg_lo:[0,1] neg_hi:[0,1]
	v_pk_add_f32 v[52:53], v[52:53], v[70:71] op_sel:[0,1] neg_lo:[0,1] neg_hi:[0,1]
; __device__ __forceinline__ unsigned cvtpk(float lo, float hi) { f32x2_t v = {lo, hi}; bf16x2_t b = __builtin_convertvector(v, bf16x2_t); return __builtin_bit_cast(unsigned, b); }
; __device__ __forceinline__ float bflo(unsigned w) { return __uint_as_float(w << 16); }
; __device__ __forceinline__ float bfhi(unsigned w) { return __uint_as_float(w & 0xffff0000u); }
; __device__ __forceinline__ void ro_item2(int it0, LAS unsigned char* lds, const bf16_t* RQ, const bf16_t* RK, const bf16_t* RV, const bf16_t* RG, const bf16_t* SPREV, const float* GN, bf16_t* MIX,
;                                          int tid, int wid, int lane) {
;     ...
;     for (int et = 0; et < 4; ++et)
; #pragma unroll
;         for (int g = 0; g < 4; ++g) {
;             const int e0 = 32 * et + 8 * g + 4 * hi;
;             const u32x2 gt = *(const u32x2*)(RG + qrow * 1024 + h * 128 + e0);
;             const f32x4 gn = *(const f32x4*)(GN + h * 128 + e0);
;             const float y0 = (o[et][4 * g] - mean) * rstd * gn[0] * bflo(gt.x), y1 = (o[et][4 * g + 1] - mean) * rstd * gn[1] * bfhi(gt.x);
;             const float y2 = (o[et][4 * g + 2] - mean) * rstd * gn[2] * bflo(gt.y), y3 = (o[et][4 * g + 3] - mean) * rstd * gn[3] * bfhi(gt.y);
;             u32x2 w; w.x = cvtpk(y0, y1); w.y = cvtpk(y2, y3);
;             *(u32x2*)(MIX + qrow * 2048 + h * 128 + e0) = w;
;         }
	v_pk_mul_f32 v[50:51], v[50:51], v[72:73] op_sel_hi:[1,0]
	v_pk_mul_f32 v[52:53], v[52:53], v[72:73] op_sel_hi:[1,0]
	v_pk_add_f32 v[54:55], v[54:55], v[70:71] op_sel:[0,1] neg_lo:[0,1] neg_hi:[0,1]
	v_pk_add_f32 v[56:57], v[56:57], v[70:71] op_sel:[0,1] neg_lo:[0,1] neg_hi:[0,1]
	v_pk_mul_f32 v[54:55], v[54:55], v[72:73] op_sel_hi:[1,0]
	v_pk_mul_f32 v[56:57], v[56:57], v[72:73] op_sel_hi:[1,0]
	v_pk_add_f32 v[58:59], v[58:59], v[70:71] op_sel:[0,1] neg_lo:[0,1] neg_hi:[0,1]
	v_pk_add_f32 v[34:35], v[34:35], v[70:71] op_sel:[0,1] neg_lo:[0,1] neg_hi:[0,1]
	v_pk_mul_f32 v[58:59], v[58:59], v[72:73] op_sel_hi:[1,0]
	v_pk_mul_f32 v[34:35], v[34:35], v[72:73] op_sel_hi:[1,0]
	v_pk_add_f32 v[36:37], v[36:37], v[70:71] op_sel:[0,1] neg_lo:[0,1] neg_hi:[0,1]
	v_pk_add_f32 v[38:39], v[38:39], v[70:71] op_sel:[0,1] neg_lo:[0,1] neg_hi:[0,1]
	v_pk_mul_f32 v[36:37], v[36:37], v[72:73] op_sel_hi:[1,0]
	v_pk_mul_f32 v[38:39], v[38:39], v[72:73] op_sel_hi:[1,0]
	v_pk_add_f32 v[18:19], v[18:19], v[70:71] op_sel:[0,1] neg_lo:[0,1] neg_hi:[0,1]
	v_pk_add_f32 v[20:21], v[20:21], v[70:71] op_sel:[0,1] neg_lo:[0,1] neg_hi:[0,1]
	v_pk_mul_f32 v[18:19], v[18:19], v[72:73] op_sel_hi:[1,0]
	v_pk_mul_f32 v[20:21], v[20:21], v[72:73] op_sel_hi:[1,0]
	v_pk_add_f32 v[22:23], v[22:23], v[70:71] op_sel:[0,1] neg_lo:[0,1] neg_hi:[0,1]
	v_pk_add_f32 v[2:3], v[2:3], v[70:71] op_sel:[0,1] neg_lo:[0,1] neg_hi:[0,1]
	v_pk_mul_f32 v[22:23], v[22:23], v[72:73] op_sel_hi:[1,0]
	v_pk_mul_f32 v[2:3], v[2:3], v[72:73] op_sel_hi:[1,0]
	v_pk_add_f32 v[4:5], v[4:5], v[70:71] op_sel:[0,1] neg_lo:[0,1] neg_hi:[0,1]
	v_pk_add_f32 v[6:7], v[6:7], v[70:71] op_sel:[0,1] neg_lo:[0,1] neg_hi:[0,1]
	v_pk_mul_f32 v[4:5], v[4:5], v[72:73] op_sel_hi:[1,0]
	v_pk_mul_f32 v[6:7], v[6:7], v[72:73] op_sel_hi:[1,0]
	s_cmpk_lt_i32 s50, 0x200
	s_waitcnt vmcnt(30)
	v_pk_mul_f32 v[50:51], v[192:193], v[50:51]
	v_lshlrev_b32_e32 v66, 16, v82
	v_and_b32_e32 v67, 0xffff0000, v82
	v_pk_mul_f32 v[50:51], v[50:51], v[66:67]
	v_pk_mul_f32 v[52:53], v[194:195], v[52:53]
	v_lshlrev_b32_e32 v66, 16, v83
	v_and_b32_e32 v67, 0xffff0000, v83
	v_pk_mul_f32 v[52:53], v[52:53], v[66:67]
	v_cvt_pk_bf16_f32 v66, v50, v51
	v_cvt_pk_bf16_f32 v67, v52, v53
	v_lshl_add_u64 v[50:51], v[78:79], 0, v[140:141]
	global_store_dwordx2 v[50:51], v[66:67], off
	s_nop 0
	s_waitcnt vmcnt(29)
	v_pk_mul_f32 v[54:55], v[196:197], v[54:55]
	v_lshlrev_b32_e32 v66, 16, v84
	v_and_b32_e32 v67, 0xffff0000, v84
	v_pk_mul_f32 v[56:57], v[198:199], v[56:57]
	v_lshlrev_b32_e32 v52, 16, v85
	v_and_b32_e32 v53, 0xffff0000, v85
	v_pk_mul_f32 v[54:55], v[54:55], v[66:67]
	v_pk_mul_f32 v[52:53], v[56:57], v[52:53]
	v_cvt_pk_bf16_f32 v54, v54, v55
	v_cvt_pk_bf16_f32 v55, v52, v53
	global_store_dwordx2 v[50:51], v[54:55], off offset:16
	s_nop 0
	s_waitcnt vmcnt(28)
	v_pk_mul_f32 v[52:53], v[200:201], v[58:59]
	v_lshlrev_b32_e32 v58, 16, v86
	v_and_b32_e32 v59, 0xffff0000, v86
	v_pk_mul_f32 v[52:53], v[52:53], v[58:59]
	v_pk_add_f32 v[58:59], v[60:61], v[70:71] op_sel:[0,1] neg_lo:[0,1] neg_hi:[0,1]
	v_lshlrev_b32_e32 v56, 16, v87
	v_pk_mul_f32 v[58:59], v[58:59], v[72:73] op_sel_hi:[1,0]
	v_and_b32_e32 v57, 0xffff0000, v87
	v_pk_mul_f32 v[54:55], v[202:203], v[58:59]
	v_cvt_pk_bf16_f32 v52, v52, v53
	v_pk_mul_f32 v[54:55], v[54:55], v[56:57]
	v_pk_add_f32 v[58:59], v[62:63], v[70:71] op_sel:[0,1] neg_lo:[0,1] neg_hi:[0,1]
	v_cvt_pk_bf16_f32 v53, v54, v55
	global_store_dwordx2 v[50:51], v[52:53], off offset:32
	s_nop 0
	v_pk_mul_f32 v[58:59], v[58:59], v[72:73] op_sel_hi:[1,0]
	s_waitcnt vmcnt(27)
	v_pk_mul_f32 v[52:53], v[204:205], v[58:59]
	v_lshlrev_b32_e32 v58, 16, v88
	v_and_b32_e32 v59, 0xffff0000, v88
	v_pk_mul_f32 v[52:53], v[52:53], v[58:59]
	v_pk_add_f32 v[58:59], v[64:65], v[70:71] op_sel:[0,1] neg_lo:[0,1] neg_hi:[0,1]
	v_lshlrev_b32_e32 v56, 16, v89
	v_pk_mul_f32 v[58:59], v[58:59], v[72:73] op_sel_hi:[1,0]
	v_and_b32_e32 v57, 0xffff0000, v89
	v_pk_mul_f32 v[54:55], v[206:207], v[58:59]
	v_cvt_pk_bf16_f32 v52, v52, v53
	v_pk_mul_f32 v[54:55], v[54:55], v[56:57]
	s_nop 0
	v_cvt_pk_bf16_f32 v53, v54, v55
	global_store_dwordx2 v[50:51], v[52:53], off offset:48
	s_nop 0
	s_waitcnt vmcnt(26)
	v_pk_mul_f32 v[34:35], v[208:209], v[34:35]
	v_lshlrev_b32_e32 v52, 16, v90
	v_and_b32_e32 v53, 0xffff0000, v90
	v_pk_mul_f32 v[34:35], v[34:35], v[52:53]
	v_pk_mul_f32 v[36:37], v[210:211], v[36:37]
	v_lshlrev_b32_e32 v52, 16, v91
	v_and_b32_e32 v53, 0xffff0000, v91
	v_pk_mul_f32 v[36:37], v[36:37], v[52:53]
	v_cvt_pk_bf16_f32 v34, v34, v35
	v_cvt_pk_bf16_f32 v35, v36, v37
	global_store_dwordx2 v[50:51], v[34:35], off offset:64
	s_nop 0
	s_waitcnt vmcnt(25)
	v_pk_mul_f32 v[34:35], v[212:213], v[38:39]
	v_lshlrev_b32_e32 v38, 16, v92
	v_and_b32_e32 v39, 0xffff0000, v92
	v_pk_mul_f32 v[34:35], v[34:35], v[38:39]
	v_pk_add_f32 v[38:39], v[40:41], v[70:71] op_sel:[0,1] neg_lo:[0,1] neg_hi:[0,1]
	v_cvt_pk_bf16_f32 v34, v34, v35
	v_pk_mul_f32 v[38:39], v[38:39], v[72:73] op_sel_hi:[1,0]
	v_pk_add_f32 v[40:41], v[42:43], v[70:71] op_sel:[0,1] neg_lo:[0,1] neg_hi:[0,1]
	v_pk_mul_f32 v[36:37], v[214:215], v[38:39]
	v_lshlrev_b32_e32 v38, 16, v93
	v_and_b32_e32 v39, 0xffff0000, v93
	v_pk_mul_f32 v[36:37], v[36:37], v[38:39]
	v_pk_mul_f32 v[40:41], v[40:41], v[72:73] op_sel_hi:[1,0]
	v_cvt_pk_bf16_f32 v35, v36, v37
	global_store_dwordx2 v[50:51], v[34:35], off offset:80
	s_nop 0
	s_waitcnt vmcnt(24)
; __device__ __forceinline__ unsigned cvtpk(float lo, float hi) { f32x2_t v = {lo, hi}; bf16x2_t b = __builtin_convertvector(v, bf16x2_t); return __builtin_bit_cast(unsigned, b); }
; __device__ __forceinline__ float bflo(unsigned w) { return __uint_as_float(w << 16); }
; __device__ __forceinline__ float bfhi(unsigned w) { return __uint_as_float(w & 0xffff0000u); }
; __device__ __forceinline__ void ro_item2(int it0, LAS unsigned char* lds, const bf16_t* RQ, const bf16_t* RK, const bf16_t* RV, const bf16_t* RG, const bf16_t* SPREV, const float* GN, bf16_t* MIX,
;                                          int tid, int wid, int lane) {
;     ...
;     for (int et = 0; et < 4; ++et)
; #pragma unroll
;         for (int g = 0; g < 4; ++g) {
;             const int e0 = 32 * et + 8 * g + 4 * hi;
;             const u32x2 gt = *(const u32x2*)(RG + qrow * 1024 + h * 128 + e0);
;             const f32x4 gn = *(const f32x4*)(GN + h * 128 + e0);
;             const float y0 = (o[et][4 * g] - mean) * rstd * gn[0] * bflo(gt.x), y1 = (o[et][4 * g + 1] - mean) * rstd * gn[1] * bfhi(gt.x);
;             const float y2 = (o[et][4 * g + 2] - mean) * rstd * gn[2] * bflo(gt.y), y3 = (o[et][4 * g + 3] - mean) * rstd * gn[3] * bfhi(gt.y);
;             u32x2 w; w.x = cvtpk(y0, y1); w.y = cvtpk(y2, y3);
;             *(u32x2*)(MIX + qrow * 2048 + h * 128 + e0) = w;
;         }
	v_pk_mul_f32 v[34:35], v[216:217], v[40:41]
	v_lshlrev_b32_e32 v40, 16, v94
	v_and_b32_e32 v41, 0xffff0000, v94
	v_pk_mul_f32 v[34:35], v[34:35], v[40:41]
	v_pk_add_f32 v[40:41], v[44:45], v[70:71] op_sel:[0,1] neg_lo:[0,1] neg_hi:[0,1]
	v_lshlrev_b32_e32 v38, 16, v95
	v_pk_mul_f32 v[40:41], v[40:41], v[72:73] op_sel_hi:[1,0]
	v_and_b32_e32 v39, 0xffff0000, v95
	v_pk_mul_f32 v[36:37], v[218:219], v[40:41]
	v_cvt_pk_bf16_f32 v34, v34, v35
	v_pk_mul_f32 v[36:37], v[36:37], v[38:39]
	v_pk_add_f32 v[40:41], v[46:47], v[70:71] op_sel:[0,1] neg_lo:[0,1] neg_hi:[0,1]
	v_cvt_pk_bf16_f32 v35, v36, v37
	global_store_dwordx2 v[50:51], v[34:35], off offset:96
	s_nop 0
	v_pk_mul_f32 v[40:41], v[40:41], v[72:73] op_sel_hi:[1,0]
	s_waitcnt vmcnt(23)
	v_pk_mul_f32 v[34:35], v[220:221], v[40:41]
	v_lshlrev_b32_e32 v40, 16, v96
	v_and_b32_e32 v41, 0xffff0000, v96
	v_pk_mul_f32 v[34:35], v[34:35], v[40:41]
	v_pk_add_f32 v[40:41], v[48:49], v[70:71] op_sel:[0,1] neg_lo:[0,1] neg_hi:[0,1]
	v_lshlrev_b32_e32 v38, 16, v97
	v_pk_mul_f32 v[40:41], v[40:41], v[72:73] op_sel_hi:[1,0]
	v_and_b32_e32 v39, 0xffff0000, v97
	v_pk_mul_f32 v[36:37], v[222:223], v[40:41]
	v_cvt_pk_bf16_f32 v34, v34, v35
	v_pk_mul_f32 v[36:37], v[36:37], v[38:39]
	s_nop 0
	v_cvt_pk_bf16_f32 v35, v36, v37
	global_store_dwordx2 v[50:51], v[34:35], off offset:112
	s_nop 0
	s_waitcnt vmcnt(22)
	v_pk_mul_f32 v[18:19], v[18:19], v[224:225]
	v_lshlrev_b32_e32 v34, 16, v98
	v_and_b32_e32 v35, 0xffff0000, v98
	v_pk_mul_f32 v[18:19], v[18:19], v[34:35]
	v_pk_mul_f32 v[20:21], v[20:21], v[226:227]
	v_lshlrev_b32_e32 v34, 16, v99
	v_and_b32_e32 v35, 0xffff0000, v99
	v_pk_mul_f32 v[20:21], v[20:21], v[34:35]
	v_cvt_pk_bf16_f32 v18, v18, v19
	v_cvt_pk_bf16_f32 v19, v20, v21
	global_store_dwordx2 v[50:51], v[18:19], off offset:128
	s_nop 0
	s_waitcnt vmcnt(21)
	v_pk_mul_f32 v[18:19], v[22:23], v[228:229]
	v_lshlrev_b32_e32 v22, 16, v100
	v_and_b32_e32 v23, 0xffff0000, v100
	v_pk_mul_f32 v[18:19], v[18:19], v[22:23]
	v_pk_add_f32 v[22:23], v[24:25], v[70:71] op_sel:[0,1] neg_lo:[0,1] neg_hi:[0,1]
	v_cvt_pk_bf16_f32 v18, v18, v19
	v_pk_mul_f32 v[22:23], v[22:23], v[72:73] op_sel_hi:[1,0]
	v_pk_add_f32 v[24:25], v[26:27], v[70:71] op_sel:[0,1] neg_lo:[0,1] neg_hi:[0,1]
	v_pk_mul_f32 v[20:21], v[22:23], v[230:231]
	v_lshlrev_b32_e32 v22, 16, v101
	v_and_b32_e32 v23, 0xffff0000, v101
	v_pk_mul_f32 v[20:21], v[20:21], v[22:23]
	v_pk_mul_f32 v[24:25], v[24:25], v[72:73] op_sel_hi:[1,0]
	v_cvt_pk_bf16_f32 v19, v20, v21
	global_store_dwordx2 v[50:51], v[18:19], off offset:144
	s_nop 0
	s_waitcnt vmcnt(20)
	v_pk_mul_f32 v[18:19], v[24:25], v[232:233]
	v_lshlrev_b32_e32 v24, 16, v102
	v_and_b32_e32 v25, 0xffff0000, v102
	v_pk_mul_f32 v[18:19], v[18:19], v[24:25]
	v_pk_add_f32 v[24:25], v[28:29], v[70:71] op_sel:[0,1] neg_lo:[0,1] neg_hi:[0,1]
	v_lshlrev_b32_e32 v22, 16, v103
	v_pk_mul_f32 v[24:25], v[24:25], v[72:73] op_sel_hi:[1,0]
	v_and_b32_e32 v23, 0xffff0000, v103
	v_pk_mul_f32 v[20:21], v[24:25], v[234:235]
	v_cvt_pk_bf16_f32 v18, v18, v19
	v_pk_mul_f32 v[20:21], v[20:21], v[22:23]
	v_pk_add_f32 v[24:25], v[30:31], v[70:71] op_sel:[0,1] neg_lo:[0,1] neg_hi:[0,1]
	v_cvt_pk_bf16_f32 v19, v20, v21
	global_store_dwordx2 v[50:51], v[18:19], off offset:160
	s_nop 0
	v_pk_mul_f32 v[24:25], v[24:25], v[72:73] op_sel_hi:[1,0]
	s_waitcnt vmcnt(19)
	v_pk_mul_f32 v[18:19], v[24:25], v[236:237]
	v_lshlrev_b32_e32 v24, 16, v104
	v_and_b32_e32 v25, 0xffff0000, v104
	v_pk_mul_f32 v[18:19], v[18:19], v[24:25]
	v_pk_add_f32 v[24:25], v[32:33], v[70:71] op_sel:[0,1] neg_lo:[0,1] neg_hi:[0,1]
	v_lshlrev_b32_e32 v22, 16, v105
	v_pk_mul_f32 v[24:25], v[24:25], v[72:73] op_sel_hi:[1,0]
	v_and_b32_e32 v23, 0xffff0000, v105
	v_pk_mul_f32 v[20:21], v[24:25], v[238:239]
	v_cvt_pk_bf16_f32 v18, v18, v19
	v_pk_mul_f32 v[20:21], v[20:21], v[22:23]
	s_nop 0
	v_cvt_pk_bf16_f32 v19, v20, v21
	global_store_dwordx2 v[50:51], v[18:19], off offset:176
	s_nop 0
	s_waitcnt vmcnt(18)
	v_pk_mul_f32 v[2:3], v[2:3], v[240:241]
	v_lshlrev_b32_e32 v18, 16, v106
	v_and_b32_e32 v19, 0xffff0000, v106
	v_pk_mul_f32 v[2:3], v[2:3], v[18:19]
	v_pk_mul_f32 v[4:5], v[4:5], v[242:243]
	v_lshlrev_b32_e32 v18, 16, v107
	v_and_b32_e32 v19, 0xffff0000, v107
	v_pk_mul_f32 v[4:5], v[4:5], v[18:19]
	v_cvt_pk_bf16_f32 v2, v2, v3
	v_cvt_pk_bf16_f32 v3, v4, v5
	global_store_dwordx2 v[50:51], v[2:3], off offset:192
	s_nop 0
	s_waitcnt vmcnt(17)
	v_pk_mul_f32 v[2:3], v[6:7], v[244:245]
	v_lshlrev_b32_e32 v6, 16, v108
	v_and_b32_e32 v7, 0xffff0000, v108
	v_pk_mul_f32 v[2:3], v[2:3], v[6:7]
	v_pk_add_f32 v[6:7], v[8:9], v[70:71] op_sel:[0,1] neg_lo:[0,1] neg_hi:[0,1]
	v_cvt_pk_bf16_f32 v2, v2, v3
	v_pk_mul_f32 v[6:7], v[6:7], v[72:73] op_sel_hi:[1,0]
	v_pk_add_f32 v[8:9], v[10:11], v[70:71] op_sel:[0,1] neg_lo:[0,1] neg_hi:[0,1]
	v_pk_mul_f32 v[4:5], v[6:7], v[246:247]
	v_lshlrev_b32_e32 v6, 16, v109
	v_and_b32_e32 v7, 0xffff0000, v109
	v_pk_mul_f32 v[4:5], v[4:5], v[6:7]
	v_pk_mul_f32 v[8:9], v[8:9], v[72:73] op_sel_hi:[1,0]
	v_cvt_pk_bf16_f32 v3, v4, v5
	global_store_dwordx2 v[50:51], v[2:3], off offset:208
	s_nop 0
	s_waitcnt vmcnt(16)
	v_pk_mul_f32 v[2:3], v[8:9], v[248:249]
	v_lshlrev_b32_e32 v8, 16, v110
	v_and_b32_e32 v9, 0xffff0000, v110
	v_pk_mul_f32 v[2:3], v[2:3], v[8:9]
	v_pk_add_f32 v[8:9], v[12:13], v[70:71] op_sel:[0,1] neg_lo:[0,1] neg_hi:[0,1]
	v_lshlrev_b32_e32 v6, 16, v111
	v_pk_mul_f32 v[8:9], v[8:9], v[72:73] op_sel_hi:[1,0]
	v_and_b32_e32 v7, 0xffff0000, v111
	v_pk_mul_f32 v[4:5], v[8:9], v[250:251]
	v_cvt_pk_bf16_f32 v2, v2, v3
	v_pk_mul_f32 v[4:5], v[4:5], v[6:7]
	v_pk_add_f32 v[8:9], v[14:15], v[70:71] op_sel:[0,1] neg_lo:[0,1] neg_hi:[0,1]
	v_cvt_pk_bf16_f32 v3, v4, v5
	global_store_dwordx2 v[50:51], v[2:3], off offset:224
	s_nop 0
	v_pk_mul_f32 v[8:9], v[8:9], v[72:73] op_sel_hi:[1,0]
	s_waitcnt vmcnt(15)
	v_pk_mul_f32 v[2:3], v[8:9], v[180:181]
	v_lshlrev_b32_e32 v8, 16, v112
	v_and_b32_e32 v9, 0xffff0000, v112
	v_pk_mul_f32 v[2:3], v[2:3], v[8:9]
	v_pk_add_f32 v[8:9], v[16:17], v[70:71] op_sel:[0,1] neg_lo:[0,1] neg_hi:[0,1]
	v_lshlrev_b32_e32 v6, 16, v113
	v_pk_mul_f32 v[8:9], v[8:9], v[72:73] op_sel_hi:[1,0]
	v_and_b32_e32 v7, 0xffff0000, v113
	v_pk_mul_f32 v[4:5], v[8:9], v[182:183]
	v_cvt_pk_bf16_f32 v2, v2, v3
	v_pk_mul_f32 v[4:5], v[4:5], v[6:7]
	s_nop 0
	v_cvt_pk_bf16_f32 v3, v4, v5
	global_store_dwordx2 v[50:51], v[2:3], off offset:240
	s_cbranch_scc0 .LBB0_1246
